# row-norm consumers read their X rows with agent-scope (sc1) loads instead of invalidating L1/L2 after the panel acquire
# speedup vs baseline: 1.0073x; 1.0039x over previous
.Lpf_ok:
.Lpf_wait:
	s_barrier

.LBB0_12:
	v_mov_b32_e32 v7, v1
	v_cmp_lt_i32_e32 vcc, v196, v195
	s_waitcnt vmcnt(29)
	v_and_b32_e32 v20, 63, v7
	v_lshlrev_b32_e32 v162, 3, v20
	v_lshl_add_u64 v[8:9], v[2:3], 0, v[162:163]
	global_load_dwordx2 v[12:13], v[8:9], off sc1
	global_load_dwordx2 v[14:15], v[8:9], off offset:512 sc1
	global_load_dwordx2 v[16:17], v[8:9], off offset:1024 sc1
	global_load_dwordx2 v[18:19], v[8:9], off offset:1536 sc1
	v_cndmask_b32_e32 v8, v194, v196, vcc
	v_cmp_lt_i32_e32 vcc, v197, v195
	v_lshlrev_b32_e32 v7, 4, v7
	v_and_b32_e32 v7, 0x3f0, v7
	v_cndmask_b32_e32 v9, v194, v197, vcc
	v_cmp_lt_i32_e32 vcc, v198, v195
	s_waitcnt vmcnt(25)
	v_lshlrev_b32_e32 v46, 2, v8
	v_lshlrev_b32_e32 v47, 2, v9
	v_cndmask_b32_e32 v10, v194, v198, vcc
	v_cmp_lt_i32_e32 vcc, v199, v195
	s_waitcnt vmcnt(23)
	v_lshlrev_b32_e32 v48, 2, v10
	v_lshlrev_b32_e32 v162, 4, v20
	v_cndmask_b32_e32 v11, v194, v199, vcc
	v_lshlrev_b32_e32 v49, 2, v11
	global_load_dwordx4 v[8:11], v7, s[68:69]
	v_cmp_lt_i32_e32 vcc, v200, v195
	v_add_u32_e32 v6, s16, v6
	v_lshl_add_u64 v[2:3], v[2:3], 0, s[40:41]
	v_cndmask_b32_e32 v21, v194, v200, vcc
	v_cmp_lt_i32_e32 vcc, v201, v195
	v_lshlrev_b32_e32 v50, 2, v21
	v_lshl_add_u64 v[20:21], v[4:5], 0, v[162:163]
	v_cndmask_b32_e32 v22, v194, v201, vcc
	v_lshlrev_b32_e32 v51, 2, v22
	v_lshl_add_u64 v[4:5], v[4:5], 0, s[24:25]
	s_waitcnt vmcnt(4)
	v_and_b32_e32 v23, 0xffff0000, v12
	s_waitcnt vmcnt(3)
	v_and_b32_e32 v25, 0xffff0000, v14
	v_lshlrev_b32_e32 v22, 16, v12
	v_lshlrev_b32_e32 v24, 16, v14
	s_waitcnt vmcnt(2)
	v_and_b32_e32 v27, 0xffff0000, v16
	s_waitcnt vmcnt(1)
	v_and_b32_e32 v29, 0xffff0000, v18
	v_mov_b32_e32 v32, v23
	v_mov_b32_e32 v33, v25
	v_lshlrev_b32_e32 v12, 16, v13
	v_lshlrev_b32_e32 v14, 16, v15
	v_lshlrev_b32_e32 v26, 16, v16
	v_lshlrev_b32_e32 v28, 16, v18
	v_mov_b32_e32 v30, v22
	v_mov_b32_e32 v31, v24
	v_mov_b32_e32 v40, v27
	v_mov_b32_e32 v41, v29
	v_pk_mul_f32 v[32:33], v[32:33], v[32:33]
	v_and_b32_e32 v13, 0xffff0000, v13
	v_and_b32_e32 v15, 0xffff0000, v15
	v_lshlrev_b32_e32 v16, 16, v17
	v_lshlrev_b32_e32 v18, 16, v19
	v_mov_b32_e32 v34, v12
	v_mov_b32_e32 v35, v14
	v_mov_b32_e32 v38, v26
	v_mov_b32_e32 v39, v28
	v_pk_mul_f32 v[40:41], v[40:41], v[40:41]
	v_pk_fma_f32 v[30:31], v[30:31], v[30:31], v[32:33]
	v_and_b32_e32 v17, 0xffff0000, v17
	v_and_b32_e32 v19, 0xffff0000, v19
	v_mov_b32_e32 v36, v13
	v_mov_b32_e32 v37, v15
	v_mov_b32_e32 v42, v16
	v_mov_b32_e32 v43, v18
	v_pk_fma_f32 v[32:33], v[38:39], v[38:39], v[40:41]
	v_pk_fma_f32 v[30:31], v[34:35], v[34:35], v[30:31]
	v_mov_b32_e32 v44, v17
	v_mov_b32_e32 v45, v19
	v_pk_fma_f32 v[32:33], v[42:43], v[42:43], v[32:33]
	v_pk_fma_f32 v[30:31], v[36:37], v[36:37], v[30:31]
	v_pk_fma_f32 v[32:33], v[44:45], v[44:45], v[32:33]
	v_add_f32_e32 v30, v30, v31
	v_add_f32_e32 v30, v30, v32
	v_add_f32_e32 v30, v30, v33
	ds_bpermute_b32 v31, v46, v30
	s_waitcnt lgkmcnt(0)
	v_add_f32_e32 v30, v30, v31
	ds_bpermute_b32 v31, v47, v30
	s_waitcnt lgkmcnt(0)
	v_add_f32_e32 v30, v30, v31
	ds_bpermute_b32 v31, v48, v30
	s_waitcnt lgkmcnt(0)
	v_add_f32_e32 v30, v30, v31
	ds_bpermute_b32 v31, v49, v30
	s_waitcnt lgkmcnt(0)
	v_add_f32_e32 v30, v30, v31
	ds_bpermute_b32 v31, v50, v30
	s_waitcnt lgkmcnt(0)
	v_add_f32_e32 v30, v30, v31
	ds_bpermute_b32 v31, v51, v30
	s_waitcnt lgkmcnt(0)
	v_add_f32_e32 v30, v30, v31
	v_fmamk_f32 v30, v30, 0x3a800000, v164
	v_mul_f32_e32 v31, 0x4b800000, v30
	v_cmp_gt_f32_e32 vcc, s18, v30
	s_nop 1
	v_cndmask_b32_e32 v30, v30, v31, vcc
	v_rsq_f32_e32 v30, v30
	s_nop 0
	v_mul_f32_e32 v31, 0x45800000, v30
	v_cndmask_b32_e32 v30, v30, v31, vcc
	v_pk_mul_f32 v[22:23], v[30:31], v[22:23] op_sel_hi:[0,1]
	v_pk_mul_f32 v[12:13], v[30:31], v[12:13] op_sel_hi:[0,1]
	s_waitcnt vmcnt(0)
	v_pk_mul_f32 v[8:9], v[8:9], v[22:23]
	v_pk_mul_f32 v[10:11], v[10:11], v[12:13]
	global_store_dwordx4 v[20:21], v[8:11], off offset:-2048
	global_load_dwordx4 v[8:11], v7, s[68:69] offset:1024
	v_pk_mul_f32 v[12:13], v[30:31], v[24:25] op_sel_hi:[0,1]
	v_pk_mul_f32 v[14:15], v[30:31], v[14:15] op_sel_hi:[0,1]
	v_cmp_lt_i32_e32 vcc, s19, v6
	s_or_b64 s[12:13], vcc, s[12:13]
	s_waitcnt vmcnt(0)
	v_pk_mul_f32 v[8:9], v[8:9], v[12:13]
	v_pk_mul_f32 v[10:11], v[10:11], v[14:15]
	global_store_dwordx4 v[20:21], v[8:11], off offset:-1024
	global_load_dwordx4 v[8:11], v7, s[68:69] offset:2048
	v_pk_mul_f32 v[12:13], v[30:31], v[26:27] op_sel_hi:[0,1]
	v_pk_mul_f32 v[14:15], v[30:31], v[16:17] op_sel_hi:[0,1]
	s_waitcnt vmcnt(0)
	v_pk_mul_f32 v[8:9], v[8:9], v[12:13]
	v_pk_mul_f32 v[10:11], v[10:11], v[14:15]
	global_store_dwordx4 v[20:21], v[8:11], off
	global_load_dwordx4 v[8:11], v7, s[68:69] offset:3072
	v_pk_mul_f32 v[12:13], v[30:31], v[28:29] op_sel_hi:[0,1]
	v_pk_mul_f32 v[14:15], v[30:31], v[18:19] op_sel_hi:[0,1]
	s_waitcnt vmcnt(0)
	v_pk_mul_f32 v[8:9], v[8:9], v[12:13]
	v_pk_mul_f32 v[10:11], v[10:11], v[14:15]
	global_store_dwordx4 v[20:21], v[8:11], off offset:1024
	s_andn2_b64 exec, exec, s[12:13]
	s_cbranch_execnz .LBB0_12

.LBB0_205:
	v_mov_b32_e32 v4, v1
	v_cmp_lt_i32_e32 vcc, v196, v195
	v_and_b32_e32 v2, 63, v4
	v_lshlrev_b32_e32 v162, 3, v2
	v_lshl_add_u64 v[2:3], s[14:15], 0, v[12:13]
	v_lshl_add_u64 v[2:3], v[2:3], 0, v[162:163]
	global_load_dwordx2 v[20:21], v[2:3], off sc1
	global_load_dwordx2 v[40:41], v[2:3], off offset:512 sc1
	global_load_dwordx2 v[24:25], v[2:3], off offset:1024 sc1
	global_load_dwordx2 v[42:43], v[2:3], off offset:1536 sc1
	global_load_dwordx2 v[30:31], v[2:3], off offset:2048 sc1
	global_load_dwordx2 v[38:39], v[2:3], off offset:2560 sc1
	global_load_dwordx2 v[22:23], v[2:3], off offset:3072 sc1
	global_load_dwordx2 v[46:47], v[2:3], off offset:3584 sc1
	v_cndmask_b32_e32 v2, v194, v196, vcc
	v_cmp_lt_i32_e32 vcc, v197, v195
	v_lshlrev_b32_e32 v11, 2, v2
	s_mul_i32 s0, s82, 5
	v_cndmask_b32_e32 v2, v194, v197, vcc
	v_cmp_lt_i32_e32 vcc, v198, v195
	s_waitcnt vmcnt(20)
	v_lshlrev_b32_e32 v74, 2, v2
	v_mov_b32_e32 v15, v163
	v_cndmask_b32_e32 v2, v194, v198, vcc
	v_cmp_lt_i32_e32 vcc, v199, v195
	v_lshlrev_b32_e32 v75, 2, v2
	s_waitcnt vmcnt(7)
	v_and_b32_e32 v33, 0xffff0000, v20
	v_cndmask_b32_e32 v2, v194, v199, vcc
	v_cmp_lt_i32_e32 vcc, v200, v195
	v_lshlrev_b32_e32 v76, 2, v2
	s_waitcnt vmcnt(6)
	v_and_b32_e32 v59, 0xffff0000, v40
	v_cndmask_b32_e32 v2, v194, v200, vcc
	v_cmp_lt_i32_e32 vcc, v201, v195
	v_lshlrev_b32_e32 v77, 2, v2
	v_lshlrev_b32_e32 v32, 16, v20
	v_cndmask_b32_e32 v2, v194, v201, vcc
	v_lshlrev_b32_e32 v78, 2, v2
	v_add_u32_e32 v2, 0xfffff000, v10
	v_lshrrev_b32_e32 v2, 10, v2
	v_add_u32_e32 v2, 1, v2
	v_cmp_lt_i32_e32 vcc, s17, v10
	v_lshlrev_b32_e32 v58, 16, v40
	v_mov_b32_e32 v52, v33
	v_cndmask_b32_e32 v2, 0, v2, vcc
	v_add_u32_e32 v5, s0, v2
	v_mov_b64_e32 v[2:3], s[40:41]
	v_mad_i64_i32 v[2:3], s[0:1], v5, s29, v[2:3]
	s_mov_b64 s[0:1], 0x3000
	s_nop 0
	v_lshl_add_u64 v[44:45], v[2:3], 0, s[0:1]
	v_lshl_add_u64 v[60:61], v[2:3], 0, s[36:37]
	v_lshlrev_b32_e32 v2, 4, v4
	v_and_b32_e32 v14, 0x3f0, v2
	v_lshl_add_u64 v[2:3], v[44:45], 0, v[14:15]
	v_lshl_add_u64 v[16:17], v[60:61], 0, v[14:15]
	global_load_dwordx4 v[2:5], v[2:3], off
	v_mov_b32_e32 v53, v59
	global_load_dwordx4 v[16:19], v[16:17], off
	v_lshlrev_b32_e32 v28, 16, v21
	global_load_dwordx4 v[6:9], v14, s[6:7]
	v_lshlrev_b32_e32 v56, 16, v41
	v_mov_b32_e32 v50, v32
	v_mov_b32_e32 v51, v58
	v_pk_mul_f32 v[52:53], v[52:53], v[52:53]
	v_and_b32_e32 v57, 0xffff0000, v41
	v_mov_b32_e32 v40, v28
	v_mov_b32_e32 v41, v56
	v_pk_fma_f32 v[50:51], v[50:51], v[50:51], v[52:53]
	v_and_b32_e32 v29, 0xffff0000, v21
	s_waitcnt vmcnt(6)
	v_and_b32_e32 v35, 0xffff0000, v30
	v_pk_fma_f32 v[40:41], v[40:41], v[40:41], v[50:51]
	s_waitcnt vmcnt(5)
	v_and_b32_e32 v51, 0xffff0000, v38
	v_lshlrev_b32_e32 v34, 16, v30
	v_mov_b32_e32 v48, v29
	v_mov_b32_e32 v49, v57
	v_lshlrev_b32_e32 v50, 16, v38
	v_mov_b32_e32 v54, v35
	v_mov_b32_e32 v55, v51
	v_lshlrev_b32_e32 v26, 16, v31
	v_pk_fma_f32 v[62:63], v[48:49], v[48:49], v[40:41]
	v_lshlrev_b32_e32 v48, 16, v39
	v_mov_b32_e32 v52, v34
	v_mov_b32_e32 v53, v50
	v_pk_mul_f32 v[54:55], v[54:55], v[54:55]
	v_and_b32_e32 v27, 0xffff0000, v31
	v_and_b32_e32 v49, 0xffff0000, v39
	v_mov_b32_e32 v38, v26
	v_mov_b32_e32 v39, v48
	v_pk_fma_f32 v[52:53], v[52:53], v[52:53], v[54:55]
	v_mov_b32_e32 v40, v27
	v_mov_b32_e32 v41, v49
	v_pk_fma_f32 v[38:39], v[38:39], v[38:39], v[52:53]
	v_and_b32_e32 v67, 0xffff0000, v24
	v_and_b32_e32 v71, 0xffff0000, v42
	v_pk_fma_f32 v[68:69], v[40:41], v[40:41], v[38:39]
	v_lshlrev_b32_e32 v66, 16, v24
	v_lshlrev_b32_e32 v70, 16, v42
	v_mov_b32_e32 v80, v67
	v_mov_b32_e32 v81, v71
	v_lshlrev_b32_e32 v64, 16, v25
	s_waitcnt vmcnt(4)
	v_lshlrev_b32_e32 v52, 16, v23
	v_and_b32_e32 v53, 0xffff0000, v23
	v_lshlrev_b32_e32 v54, 16, v22
	v_and_b32_e32 v55, 0xffff0000, v22
	v_mov_b32_e32 v72, v66
	v_mov_b32_e32 v73, v70
	v_pk_mul_f32 v[80:81], v[80:81], v[80:81]
	v_and_b32_e32 v65, 0xffff0000, v25
	v_mov_b32_e32 v42, v64
	v_pk_fma_f32 v[72:73], v[72:73], v[72:73], v[80:81]
	v_mov_b32_e32 v84, v55
	v_mov_b32_e32 v82, v54
	v_mov_b32_e32 v80, v53
	v_add_u32_e32 v10, s16, v10
	s_waitcnt vmcnt(1)
	v_pk_add_f32 v[20:21], v[16:17], 1.0 op_sel_hi:[1,0]
	v_lshl_add_u64 v[16:17], s[18:19], 0, v[12:13]
	v_lshl_add_u64 v[16:17], v[16:17], 0, v[162:163]
	v_or_b32_e32 v162, 0x400, v14
	v_lshl_add_u64 v[36:37], v[44:45], 0, v[162:163]
	v_lshl_add_u64 v[30:31], v[60:61], 0, v[162:163]
	v_or_b32_e32 v162, 0x800, v14
	v_lshl_add_u64 v[40:41], v[44:45], 0, v[162:163]
	v_lshl_add_u64 v[38:39], v[60:61], 0, v[162:163]
	v_or_b32_e32 v162, 0xc00, v14
	v_lshl_add_u64 v[22:23], v[60:61], 0, v[162:163]
	v_lshlrev_b32_e32 v60, 16, v43
	v_and_b32_e32 v61, 0xffff0000, v43
	v_mov_b32_e32 v43, v60
	v_lshl_add_u64 v[24:25], v[44:45], 0, v[162:163]
	v_mov_b32_e32 v44, v65
	v_mov_b32_e32 v45, v61
	v_pk_fma_f32 v[42:43], v[42:43], v[42:43], v[72:73]
	v_pk_add_f32 v[18:19], v[18:19], 1.0 op_sel_hi:[1,0]
	v_pk_fma_f32 v[72:73], v[44:45], v[44:45], v[42:43]
	v_and_b32_e32 v45, 0xffff0000, v46
	v_lshlrev_b32_e32 v44, 16, v46
	v_mov_b32_e32 v85, v45
	v_lshlrev_b32_e32 v42, 16, v47
	v_mov_b32_e32 v83, v44
	v_pk_mul_f32 v[84:85], v[84:85], v[84:85]
	v_and_b32_e32 v43, 0xffff0000, v47
	v_mov_b32_e32 v46, v52
	v_mov_b32_e32 v47, v42
	v_pk_fma_f32 v[82:83], v[82:83], v[82:83], v[84:85]
	v_mov_b32_e32 v81, v43
	v_pk_fma_f32 v[46:47], v[46:47], v[46:47], v[82:83]
	s_add_u32 s18, s18, s24
	v_pk_fma_f32 v[46:47], v[80:81], v[80:81], v[46:47]
	v_mov_b32_e32 v80, v68
	v_mov_b32_e32 v81, v62
	v_mov_b32_e32 v62, v69
	v_pk_add_f32 v[62:63], v[80:81], v[62:63]
	v_mov_b32_e32 v68, v46
	v_mov_b32_e32 v69, v72
	v_pk_add_f32 v[62:63], v[62:63], v[68:69]
	v_mov_b32_e32 v72, v47
	v_pk_add_f32 v[46:47], v[62:63], v[72:73]
	ds_bpermute_b32 v63, v11, v47
	ds_bpermute_b32 v62, v11, v46
	s_addc_u32 s19, s19, s25
	s_add_u32 s14, s14, s24
	s_addc_u32 s15, s15, s25
	s_waitcnt lgkmcnt(0)
	v_pk_add_f32 v[46:47], v[46:47], v[62:63]
	ds_bpermute_b32 v63, v74, v47
	ds_bpermute_b32 v62, v74, v46
	s_waitcnt lgkmcnt(0)
	v_pk_add_f32 v[46:47], v[46:47], v[62:63]
	ds_bpermute_b32 v63, v75, v47
	ds_bpermute_b32 v62, v75, v46
	s_waitcnt lgkmcnt(0)
	v_pk_add_f32 v[46:47], v[46:47], v[62:63]
	ds_bpermute_b32 v63, v76, v47
	ds_bpermute_b32 v62, v76, v46
	s_waitcnt lgkmcnt(0)
	v_pk_add_f32 v[46:47], v[46:47], v[62:63]
	ds_bpermute_b32 v63, v77, v47
	ds_bpermute_b32 v62, v77, v46
	s_waitcnt lgkmcnt(0)
	v_pk_add_f32 v[46:47], v[46:47], v[62:63]
	ds_bpermute_b32 v63, v78, v47
	ds_bpermute_b32 v62, v78, v46
	s_waitcnt lgkmcnt(0)
	v_pk_add_f32 v[46:47], v[46:47], v[62:63]
	s_nop 0
	v_pk_fma_f32 v[62:63], v[46:47], s[30:31], v[164:165] op_sel_hi:[1,0,0]
	s_nop 0
	v_mul_f32_e32 v11, 0x4b800000, v63
	v_cmp_gt_f32_e64 s[38:39], s50, v63
	v_cmp_gt_f32_e32 vcc, s50, v62
	s_nop 0
	v_cndmask_b32_e64 v11, v63, v11, s[38:39]
	v_rsq_f32_e32 v11, v11
	s_nop 0
	v_mul_f32_e32 v15, 0x45800000, v11
	v_cndmask_b32_e64 v68, v11, v15, s[38:39]
	v_mul_f32_e32 v11, 0x4b800000, v62
	v_cndmask_b32_e32 v11, v62, v11, vcc
	v_rsq_f32_e32 v11, v11
	v_pk_mul_f32 v[72:73], v[68:69], v[58:59] op_sel_hi:[0,1]
	v_pk_mul_f32 v[32:33], v[68:69], v[32:33] op_sel_hi:[0,1]
	s_waitcnt vmcnt(0)
	v_pk_mul_f32 v[32:33], v[6:7], v[32:33]
	v_mul_f32_e32 v15, 0x45800000, v11
	v_cndmask_b32_e32 v58, v11, v15, vcc
	v_pk_mul_f32 v[34:35], v[58:59], v[34:35] op_sel_hi:[0,1]
	v_pk_mul_f32 v[6:7], v[6:7], v[34:35]
	v_pk_fma_f32 v[32:33], v[32:33], v[20:21], v[2:3]
	v_pk_mul_f32 v[28:29], v[68:69], v[28:29] op_sel_hi:[0,1]
	v_pk_fma_f32 v[2:3], v[20:21], v[6:7], v[2:3]
	v_pk_mul_f32 v[6:7], v[58:59], v[26:27] op_sel_hi:[0,1]
	v_pk_mul_f32 v[28:29], v[8:9], v[28:29]
	v_pk_mul_f32 v[6:7], v[8:9], v[6:7]
	v_pk_fma_f32 v[28:29], v[28:29], v[18:19], v[4:5]
	v_pk_fma_f32 v[4:5], v[18:19], v[6:7], v[4:5]
	v_cvt_pk_bf16_f32 v32, v32, v33
	v_cvt_pk_bf16_f32 v33, v28, v29
	v_cvt_pk_bf16_f32 v2, v2, v3
	v_cvt_pk_bf16_f32 v3, v4, v5
	global_store_dwordx2 v[16:17], v[32:33], off
	global_store_dwordx2 v[16:17], v[2:3], off offset:2048
	global_load_dwordx4 v[2:5], v14, s[6:7] offset:1024
	s_nop 0
	global_load_dwordx4 v[6:9], v[36:37], off
	global_load_dwordx4 v[18:21], v[30:31], off
	v_pk_mul_f32 v[74:75], v[68:69], v[56:57] op_sel_hi:[0,1]
	v_pk_mul_f32 v[26:27], v[58:59], v[50:51] op_sel_hi:[0,1]
	v_pk_mul_f32 v[34:35], v[58:59], v[48:49] op_sel_hi:[0,1]
	v_pk_mul_f32 v[56:57], v[68:69], v[66:67] op_sel_hi:[0,1]
	v_pk_mul_f32 v[46:47], v[68:69], v[64:65] op_sel_hi:[0,1]
	v_pk_mul_f32 v[48:49], v[58:59], v[54:55] op_sel_hi:[0,1]
	v_pk_mul_f32 v[50:51], v[58:59], v[52:53] op_sel_hi:[0,1]
	v_pk_mul_f32 v[32:33], v[68:69], v[70:71] op_sel_hi:[0,1]
	v_pk_mul_f32 v[28:29], v[68:69], v[60:61] op_sel_hi:[0,1]
	v_cmp_lt_i32_e32 vcc, s51, v10
	s_or_b64 s[12:13], vcc, s[12:13]
	s_waitcnt vmcnt(2)
	v_pk_mul_f32 v[30:31], v[72:73], v[2:3]
	v_pk_mul_f32 v[36:37], v[74:75], v[4:5]
	s_waitcnt vmcnt(0)
	v_pk_add_f32 v[18:19], v[18:19], 1.0 op_sel_hi:[1,0]
	v_pk_add_f32 v[20:21], v[20:21], 1.0 op_sel_hi:[1,0]
	v_pk_mul_f32 v[2:3], v[2:3], v[26:27]
	v_pk_mul_f32 v[4:5], v[4:5], v[34:35]
	v_pk_fma_f32 v[30:31], v[30:31], v[18:19], v[6:7]
	v_pk_fma_f32 v[36:37], v[36:37], v[20:21], v[8:9]
	v_pk_fma_f32 v[2:3], v[18:19], v[2:3], v[6:7]
	v_pk_fma_f32 v[4:5], v[20:21], v[4:5], v[8:9]
	v_cvt_pk_bf16_f32 v30, v30, v31
	v_cvt_pk_bf16_f32 v31, v36, v37
	v_cvt_pk_bf16_f32 v2, v2, v3
	v_cvt_pk_bf16_f32 v3, v4, v5
	global_store_dwordx2 v[16:17], v[30:31], off offset:512
	global_store_dwordx2 v[16:17], v[2:3], off offset:2560
	global_load_dwordx4 v[2:5], v14, s[6:7] offset:2048
	s_nop 0
	global_load_dwordx4 v[6:9], v[40:41], off
	global_load_dwordx4 v[18:21], v[38:39], off
	s_waitcnt vmcnt(2)
	v_pk_mul_f32 v[26:27], v[56:57], v[2:3]
	v_pk_mul_f32 v[30:31], v[46:47], v[4:5]
	s_waitcnt vmcnt(0)
	v_pk_add_f32 v[18:19], v[18:19], 1.0 op_sel_hi:[1,0]
	v_pk_add_f32 v[20:21], v[20:21], 1.0 op_sel_hi:[1,0]
	v_pk_mul_f32 v[2:3], v[48:49], v[2:3]
	v_pk_mul_f32 v[4:5], v[50:51], v[4:5]
	v_pk_fma_f32 v[26:27], v[26:27], v[18:19], v[6:7]
	v_pk_fma_f32 v[30:31], v[30:31], v[20:21], v[8:9]
	v_pk_fma_f32 v[2:3], v[2:3], v[18:19], v[6:7]
	v_pk_fma_f32 v[4:5], v[4:5], v[20:21], v[8:9]
	v_cvt_pk_bf16_f32 v26, v26, v27
	v_cvt_pk_bf16_f32 v27, v30, v31
	v_cvt_pk_bf16_f32 v2, v2, v3
	v_cvt_pk_bf16_f32 v3, v4, v5
	global_store_dwordx2 v[16:17], v[26:27], off offset:1024
	global_store_dwordx2 v[16:17], v[2:3], off offset:3072
	global_load_dwordx4 v[2:5], v14, s[6:7] offset:3072
	s_nop 0
	global_load_dwordx4 v[6:9], v[24:25], off
	global_load_dwordx4 v[18:21], v[22:23], off
	s_waitcnt vmcnt(2)
	v_pk_mul_f32 v[14:15], v[32:33], v[2:3]
	v_pk_mul_f32 v[22:23], v[28:29], v[4:5]
	s_waitcnt vmcnt(0)
	v_pk_add_f32 v[18:19], v[18:19], 1.0 op_sel_hi:[1,0]
	v_pk_add_f32 v[20:21], v[20:21], 1.0 op_sel_hi:[1,0]
	v_pk_fma_f32 v[14:15], v[14:15], v[18:19], v[6:7]
	v_pk_fma_f32 v[22:23], v[22:23], v[20:21], v[8:9]
	v_cvt_pk_bf16_f32 v14, v14, v15
	v_cvt_pk_bf16_f32 v15, v22, v23
	global_store_dwordx2 v[16:17], v[14:15], off offset:1536
	v_pk_mul_f32 v[14:15], v[58:59], v[44:45] op_sel_hi:[0,1]
	v_pk_mul_f32 v[2:3], v[14:15], v[2:3]
	s_nop 0
	v_pk_fma_f32 v[2:3], v[2:3], v[18:19], v[6:7]
	v_pk_mul_f32 v[6:7], v[58:59], v[42:43] op_sel_hi:[0,1]
	v_pk_mul_f32 v[4:5], v[6:7], v[4:5]
	v_cvt_pk_bf16_f32 v2, v2, v3
	v_pk_fma_f32 v[4:5], v[4:5], v[20:21], v[8:9]
	s_nop 0
	v_cvt_pk_bf16_f32 v3, v4, v5
	global_store_dwordx2 v[16:17], v[2:3], off offset:3584
	s_andn2_b64 exec, exec, s[12:13]
	s_cbranch_execnz .LBB0_205

.LBB0_645:
	s_or_saveexec_b64 s[8:9], s[8:9]
	v_readlane_b32 s68, v254, 60
	v_and_b32_e32 v2, 63, v2
	v_readlane_b32 s74, v252, 2
	v_readlane_b32 s75, v252, 3
	v_lshlrev_b32_e32 v162, 3, v2
	v_readlane_b32 s69, v254, 61
	v_lshl_add_u64 v[2:3], s[74:75], 0, v[36:37]
	v_lshl_add_u64 v[42:43], v[2:3], 0, v[162:163]
	v_readlane_b32 s70, v254, 62
	v_readlane_b32 s71, v254, 63
	v_readlane_b32 s72, v252, 0
	v_readlane_b32 s73, v252, 1
	s_xor_b64 exec, exec, s[8:9]
	s_cbranch_execz .LBB0_647
	global_load_dwordx2 v[2:3], v[42:43], off sc1
	s_waitcnt vmcnt(0)
	v_lshlrev_b32_e32 v14, 16, v2
	v_and_b32_e32 v15, 0xffff0000, v2
	v_lshlrev_b32_e32 v16, 16, v3
	v_and_b32_e32 v17, 0xffff0000, v3

.LBB0_650:
	global_load_dwordx2 v[2:3], v[42:43], off offset:512 sc1
	s_waitcnt vmcnt(0)
	v_lshlrev_b32_e32 v10, 16, v2
	v_and_b32_e32 v11, 0xffff0000, v2
	v_lshlrev_b32_e32 v12, 16, v3
	v_and_b32_e32 v13, 0xffff0000, v3

.LBB0_654:
	global_load_dwordx2 v[2:3], v[42:43], off offset:1024 sc1
	s_waitcnt vmcnt(0)
	v_lshlrev_b32_e32 v6, 16, v2
	v_and_b32_e32 v7, 0xffff0000, v2
	v_lshlrev_b32_e32 v8, 16, v3
	v_and_b32_e32 v9, 0xffff0000, v3

.LBB0_658:
	global_load_dwordx2 v[4:5], v[42:43], off offset:1536 sc1
	s_waitcnt vmcnt(0)
	v_lshlrev_b32_e32 v2, 16, v4
	v_and_b32_e32 v3, 0xffff0000, v4
	v_lshlrev_b32_e32 v4, 16, v5
	v_and_b32_e32 v5, 0xffff0000, v5

.LBB0_662:
	global_load_dwordx2 v[18:19], v[42:43], off offset:2048 sc1
	s_waitcnt vmcnt(0)
	v_lshlrev_b32_e32 v30, 16, v18
	v_and_b32_e32 v31, 0xffff0000, v18
	v_lshlrev_b32_e32 v32, 16, v19
	v_and_b32_e32 v33, 0xffff0000, v19

.LBB0_666:
	global_load_dwordx2 v[18:19], v[42:43], off offset:2560 sc1
	s_waitcnt vmcnt(0)
	v_lshlrev_b32_e32 v26, 16, v18
	v_and_b32_e32 v27, 0xffff0000, v18
	v_lshlrev_b32_e32 v28, 16, v19
	v_and_b32_e32 v29, 0xffff0000, v19

.LBB0_670:
	global_load_dwordx2 v[18:19], v[42:43], off offset:3072 sc1
	s_waitcnt vmcnt(0)
	v_lshlrev_b32_e32 v22, 16, v18
	v_and_b32_e32 v23, 0xffff0000, v18
	v_lshlrev_b32_e32 v24, 16, v19
	v_and_b32_e32 v25, 0xffff0000, v19

.LBB0_674:
	global_load_dwordx2 v[20:21], v[42:43], off offset:3584 sc1
	s_waitcnt vmcnt(0)
	v_lshlrev_b32_e32 v18, 16, v20
	v_and_b32_e32 v19, 0xffff0000, v20
	v_lshlrev_b32_e32 v20, 16, v21
	v_and_b32_e32 v21, 0xffff0000, v21
	s_branch .LBB0_642
